# leading-half epilogue priority raised to 3 (held through next-unit first load segment)
# speedup vs baseline: 1.0010x; 1.0010x over previous
.LBB0_384:
	ds_read_b128 v[134:137], v199
	ds_read_b128 v[138:141], v200
	ds_read_b128 v[142:145], v201
	ds_read_b128 v[146:149], v202
	ds_read_b128 v[150:153], v203
	ds_read_b128 v[174:177], v204
	ds_read_b128 v[178:181], v205
	ds_read_b128 v[182:185], v206
	s_add_u32 s24, s4, vcc_lo
	s_addc_u32 s25, s5, vcc_hi
	s_add_u32 s24, s24, 0x100
	s_addc_u32 s25, s25, 0
	s_add_u32 s82, s39, vcc_lo
	s_addc_u32 s83, s67, vcc_hi
	s_cmpk_eq_i32 vcc_lo, 0x700
	s_cselect_b32 s87, s29, s83
	s_cselect_b32 s86, s38, s82
	s_cselect_b32 s83, s34, s25
	s_cselect_b32 s82, s35, s24
	v_lshl_add_u64 v[154:155], v[132:133], 0, vcc
	v_lshl_add_u64 v[250:251], v[154:155], 0, s[48:49]
	s_add_i32 m0, s79, 0x8000
	s_mov_b64 s[24:25], 0x20080
	ds_read_b128 v[218:221], v207
	ds_read_b128 v[222:225], v207 offset:2048
	ds_read_b128 v[226:229], v208
	ds_read_b128 v[230:233], v208 offset:2048
	ds_read_b128 v[234:237], v207 offset:4096
	ds_read_b128 v[238:241], v207 offset:6144
	ds_read_b128 v[242:245], v208 offset:4096
	ds_read_b128 v[246:249], v208 offset:6144
	global_load_lds_dwordx4 v[250:251], off
	v_lshl_add_u64 v[250:251], v[154:155], 0, s[24:25]
	s_add_i32 m0, s79, 0xa000
	s_mov_b64 s[24:25], 0x60080
	global_load_lds_dwordx4 v[250:251], off
	v_lshl_add_u64 v[250:251], v[154:155], 0, s[50:51]
	s_add_i32 m0, s79, 0xc000
	v_lshl_add_u64 v[154:155], v[154:155], 0, s[24:25]
	global_load_lds_dwordx4 v[250:251], off
	s_add_i32 m0, s79, 0xe000
	s_nop 0
	global_load_lds_dwordx4 v[154:155], off
	s_waitcnt vmcnt(8)
	s_waitcnt lgkmcnt(0)
	s_barrier
	v_mfma_f32_16x16x32_bf16 v[128:131], v[134:137], v[218:221], v[128:131]
	v_mfma_f32_16x16x32_bf16 v[128:131], v[138:141], v[226:229], v[128:131]
	v_mfma_f32_16x16x32_bf16 v[112:115], v[138:141], v[230:233], v[112:115]
	v_mfma_f32_16x16x32_bf16 v[112:115], v[134:137], v[222:225], v[112:115]
	v_mfma_f32_16x16x32_bf16 v[96:99], v[134:137], v[234:237], v[96:99]
	v_mfma_f32_16x16x32_bf16 v[96:99], v[138:141], v[242:245], v[96:99]
	v_mfma_f32_16x16x32_bf16 v[80:83], v[138:141], v[246:249], v[80:83]
	v_mfma_f32_16x16x32_bf16 v[80:83], v[134:137], v[238:241], v[80:83]
	v_mfma_f32_16x16x32_bf16 v[76:79], v[142:145], v[238:241], v[76:79]
	v_mfma_f32_16x16x32_bf16 v[76:79], v[146:149], v[246:249], v[76:79]
	v_mfma_f32_16x16x32_bf16 v[92:95], v[146:149], v[242:245], v[92:95]
	v_mfma_f32_16x16x32_bf16 v[92:95], v[142:145], v[234:237], v[92:95]
	v_mfma_f32_16x16x32_bf16 v[108:111], v[142:145], v[222:225], v[108:111]
	v_mfma_f32_16x16x32_bf16 v[108:111], v[146:149], v[230:233], v[108:111]
	v_mfma_f32_16x16x32_bf16 v[124:127], v[146:149], v[226:229], v[124:127]
	v_mfma_f32_16x16x32_bf16 v[124:127], v[142:145], v[218:221], v[124:127]
	v_mfma_f32_16x16x32_bf16 v[120:123], v[150:153], v[218:221], v[120:123]
	v_mfma_f32_16x16x32_bf16 v[120:123], v[174:177], v[226:229], v[120:123]
	v_mfma_f32_16x16x32_bf16 v[104:107], v[174:177], v[230:233], v[104:107]
	v_mfma_f32_16x16x32_bf16 v[104:107], v[150:153], v[222:225], v[104:107]
	v_mfma_f32_16x16x32_bf16 v[88:91], v[150:153], v[234:237], v[88:91]
	v_mfma_f32_16x16x32_bf16 v[88:91], v[174:177], v[242:245], v[88:91]
	v_mfma_f32_16x16x32_bf16 v[72:75], v[174:177], v[246:249], v[72:75]
	v_mfma_f32_16x16x32_bf16 v[72:75], v[150:153], v[238:241], v[72:75]
	v_mfma_f32_16x16x32_bf16 v[68:71], v[178:181], v[238:241], v[68:71]
	v_mfma_f32_16x16x32_bf16 v[68:71], v[182:185], v[246:249], v[68:71]
	v_mfma_f32_16x16x32_bf16 v[84:87], v[182:185], v[242:245], v[84:87]
	v_mfma_f32_16x16x32_bf16 v[84:87], v[178:181], v[234:237], v[84:87]
	v_mfma_f32_16x16x32_bf16 v[100:103], v[178:181], v[222:225], v[100:103]
	v_mfma_f32_16x16x32_bf16 v[100:103], v[182:185], v[230:233], v[100:103]
	v_mfma_f32_16x16x32_bf16 v[116:119], v[182:185], v[226:229], v[116:119]
	v_mfma_f32_16x16x32_bf16 v[116:119], v[178:181], v[218:221], v[116:119]
	s_barrier
	s_add_i32 s24, s1, s77
	v_lshl_add_u64 v[154:155], s[86:87], 0, v[158:159]
	s_mov_b32 m0, s24
	ds_read_b128 v[218:221], v207 offset:16384
	ds_read_b128 v[222:225], v207 offset:18432
	ds_read_b128 v[226:229], v208 offset:16384
	ds_read_b128 v[230:233], v208 offset:18432
	ds_read_b128 v[234:237], v207 offset:20480
	ds_read_b128 v[238:241], v207 offset:22528
	ds_read_b128 v[242:245], v208 offset:20480
	ds_read_b128 v[246:249], v208 offset:22528
	global_load_lds_dwordx4 v[154:155], off
	v_lshl_add_u64 v[250:251], v[154:155], 0, s[14:15]
	s_add_i32 m0, s24, 0x2000
	s_add_i32 s24, s12, s77
	global_load_lds_dwordx4 v[250:251], off
	v_lshl_add_u64 v[250:251], v[154:155], 0, s[16:17]
	s_mov_b32 m0, s24
	s_nop 0
	global_load_lds_dwordx4 v[250:251], off
	v_lshl_add_u64 v[250:251], v[154:155], 0, s[18:19]
	s_add_i32 m0, s24, 0x2000
	s_nop 0
	global_load_lds_dwordx4 v[250:251], off
	s_waitcnt vmcnt(4)
	s_waitcnt lgkmcnt(0)
	s_barrier
	v_mfma_f32_16x16x32_bf16 v[64:67], v[134:137], v[218:221], v[64:67]
	v_mfma_f32_16x16x32_bf16 v[64:67], v[138:141], v[226:229], v[64:67]
	v_mfma_f32_16x16x32_bf16 v[48:51], v[138:141], v[230:233], v[48:51]
	v_mfma_f32_16x16x32_bf16 v[48:51], v[134:137], v[222:225], v[48:51]
	v_mfma_f32_16x16x32_bf16 v[32:35], v[134:137], v[234:237], v[32:35]
	v_mfma_f32_16x16x32_bf16 v[32:35], v[138:141], v[242:245], v[32:35]
	v_mfma_f32_16x16x32_bf16 v[16:19], v[138:141], v[246:249], v[16:19]
	v_mfma_f32_16x16x32_bf16 v[16:19], v[134:137], v[238:241], v[16:19]
	v_mfma_f32_16x16x32_bf16 v[12:15], v[142:145], v[238:241], v[12:15]
	v_mfma_f32_16x16x32_bf16 v[12:15], v[146:149], v[246:249], v[12:15]
	v_mfma_f32_16x16x32_bf16 v[28:31], v[146:149], v[242:245], v[28:31]
	v_mfma_f32_16x16x32_bf16 v[28:31], v[142:145], v[234:237], v[28:31]
	v_mfma_f32_16x16x32_bf16 v[44:47], v[142:145], v[222:225], v[44:47]
	v_mfma_f32_16x16x32_bf16 v[44:47], v[146:149], v[230:233], v[44:47]
	v_mfma_f32_16x16x32_bf16 v[60:63], v[146:149], v[226:229], v[60:63]
	v_mfma_f32_16x16x32_bf16 v[60:63], v[142:145], v[218:221], v[60:63]
	v_mfma_f32_16x16x32_bf16 v[56:59], v[150:153], v[218:221], v[56:59]
	v_mfma_f32_16x16x32_bf16 v[56:59], v[174:177], v[226:229], v[56:59]
	v_mfma_f32_16x16x32_bf16 v[40:43], v[174:177], v[230:233], v[40:43]
	v_mfma_f32_16x16x32_bf16 v[40:43], v[150:153], v[222:225], v[40:43]
	v_mfma_f32_16x16x32_bf16 v[24:27], v[150:153], v[234:237], v[24:27]
	v_mfma_f32_16x16x32_bf16 v[24:27], v[174:177], v[242:245], v[24:27]
	v_mfma_f32_16x16x32_bf16 v[8:11], v[174:177], v[246:249], v[8:11]
	v_mfma_f32_16x16x32_bf16 v[8:11], v[150:153], v[238:241], v[8:11]
	v_mfma_f32_16x16x32_bf16 v[4:7], v[178:181], v[238:241], v[4:7]
	v_mfma_f32_16x16x32_bf16 v[4:7], v[182:185], v[246:249], v[4:7]
	v_mfma_f32_16x16x32_bf16 v[20:23], v[182:185], v[242:245], v[20:23]
	v_mfma_f32_16x16x32_bf16 v[20:23], v[178:181], v[234:237], v[20:23]
	v_mfma_f32_16x16x32_bf16 v[36:39], v[178:181], v[222:225], v[36:39]
	v_mfma_f32_16x16x32_bf16 v[36:39], v[182:185], v[230:233], v[36:39]
	v_mfma_f32_16x16x32_bf16 v[52:55], v[182:185], v[226:229], v[52:55]
	v_mfma_f32_16x16x32_bf16 v[52:55], v[178:181], v[218:221], v[52:55]
	s_barrier
	ds_read_b128 v[134:137], v213
	ds_read_b128 v[138:141], v214
	ds_read_b128 v[142:145], v209
	ds_read_b128 v[146:149], v210
	ds_read_b128 v[150:153], v215
	ds_read_b128 v[174:177], v216
	ds_read_b128 v[178:181], v211
	ds_read_b128 v[182:185], v212
	s_mov_b32 m0, s79
	v_lshl_add_u64 v[250:251], s[82:83], 0, v[0:1]
	ds_read_b128 v[218:221], v207 offset:32768
	ds_read_b128 v[222:225], v207 offset:34816
	ds_read_b128 v[226:229], v208 offset:32768
	ds_read_b128 v[230:233], v208 offset:34816
	ds_read_b128 v[234:237], v207 offset:36864
	ds_read_b128 v[238:241], v207 offset:38912
	ds_read_b128 v[242:245], v208 offset:36864
	ds_read_b128 v[246:249], v208 offset:38912
	global_load_lds_dwordx4 v[250:251], off
	v_lshl_add_u64 v[252:253], v[250:251], 0, s[20:21]
	s_mov_b32 m0, s81
	s_nop 0
	global_load_lds_dwordx4 v[252:253], off
	v_lshl_add_u64 v[252:253], v[250:251], 0, s[14:15]
	s_mov_b32 m0, s97
	v_lshl_add_u64 v[250:251], v[250:251], 0, s[22:23]
	global_load_lds_dwordx4 v[252:253], off
	s_mov_b32 m0, s64
	s_nop 0
	global_load_lds_dwordx4 v[250:251], off
	s_waitcnt vmcnt(8)
	s_waitcnt lgkmcnt(0)
	s_barrier
	v_mfma_f32_16x16x32_bf16 v[128:131], v[134:137], v[218:221], v[128:131]
	v_mfma_f32_16x16x32_bf16 v[128:131], v[138:141], v[226:229], v[128:131]
	v_mfma_f32_16x16x32_bf16 v[112:115], v[138:141], v[230:233], v[112:115]
	v_mfma_f32_16x16x32_bf16 v[112:115], v[134:137], v[222:225], v[112:115]
	v_mfma_f32_16x16x32_bf16 v[96:99], v[134:137], v[234:237], v[96:99]
	v_mfma_f32_16x16x32_bf16 v[96:99], v[138:141], v[242:245], v[96:99]
	v_mfma_f32_16x16x32_bf16 v[80:83], v[138:141], v[246:249], v[80:83]
	v_mfma_f32_16x16x32_bf16 v[80:83], v[134:137], v[238:241], v[80:83]
	v_mfma_f32_16x16x32_bf16 v[76:79], v[142:145], v[238:241], v[76:79]
	v_mfma_f32_16x16x32_bf16 v[76:79], v[146:149], v[246:249], v[76:79]
	v_mfma_f32_16x16x32_bf16 v[92:95], v[146:149], v[242:245], v[92:95]
	v_mfma_f32_16x16x32_bf16 v[92:95], v[142:145], v[234:237], v[92:95]
	v_mfma_f32_16x16x32_bf16 v[108:111], v[142:145], v[222:225], v[108:111]
	v_mfma_f32_16x16x32_bf16 v[108:111], v[146:149], v[230:233], v[108:111]
	v_mfma_f32_16x16x32_bf16 v[124:127], v[146:149], v[226:229], v[124:127]
	v_mfma_f32_16x16x32_bf16 v[124:127], v[142:145], v[218:221], v[124:127]
	v_mfma_f32_16x16x32_bf16 v[120:123], v[150:153], v[218:221], v[120:123]
	v_mfma_f32_16x16x32_bf16 v[120:123], v[174:177], v[226:229], v[120:123]
	v_mfma_f32_16x16x32_bf16 v[104:107], v[174:177], v[230:233], v[104:107]
	v_mfma_f32_16x16x32_bf16 v[104:107], v[150:153], v[222:225], v[104:107]
	v_mfma_f32_16x16x32_bf16 v[88:91], v[150:153], v[234:237], v[88:91]
	v_mfma_f32_16x16x32_bf16 v[88:91], v[174:177], v[242:245], v[88:91]
	v_mfma_f32_16x16x32_bf16 v[72:75], v[174:177], v[246:249], v[72:75]
	v_mfma_f32_16x16x32_bf16 v[72:75], v[150:153], v[238:241], v[72:75]
	v_mfma_f32_16x16x32_bf16 v[68:71], v[178:181], v[238:241], v[68:71]
	v_mfma_f32_16x16x32_bf16 v[68:71], v[182:185], v[246:249], v[68:71]
	v_mfma_f32_16x16x32_bf16 v[84:87], v[182:185], v[242:245], v[84:87]
	v_mfma_f32_16x16x32_bf16 v[84:87], v[178:181], v[234:237], v[84:87]
	v_mfma_f32_16x16x32_bf16 v[100:103], v[178:181], v[222:225], v[100:103]
	v_mfma_f32_16x16x32_bf16 v[100:103], v[182:185], v[230:233], v[100:103]
	v_mfma_f32_16x16x32_bf16 v[116:119], v[182:185], v[226:229], v[116:119]
	v_mfma_f32_16x16x32_bf16 v[116:119], v[178:181], v[218:221], v[116:119]
	s_barrier
	s_add_i32 s24, s70, s77
	v_lshl_add_u64 v[250:251], v[154:155], 0, s[48:49]
	s_mov_b32 m0, s24
	ds_read_b128 v[218:221], v207 offset:49152
	ds_read_b128 v[222:225], v207 offset:51200
	ds_read_b128 v[226:229], v208 offset:49152
	ds_read_b128 v[230:233], v208 offset:51200
	ds_read_b128 v[234:237], v207 offset:53248
	ds_read_b128 v[238:241], v207 offset:55296
	ds_read_b128 v[242:245], v208 offset:53248
	ds_read_b128 v[246:249], v208 offset:55296
	global_load_lds_dwordx4 v[250:251], off
	v_lshl_add_u64 v[250:251], v[154:155], 0, s[50:51]
	s_add_i32 m0, s24, 0x2000
	s_add_i32 s24, s71, s77
	global_load_lds_dwordx4 v[250:251], off
	v_lshl_add_u64 v[250:251], v[154:155], 0, s[52:53]
	s_mov_b32 m0, s24
	v_lshl_add_u64 v[154:155], v[154:155], 0, s[54:55]
	global_load_lds_dwordx4 v[250:251], off
	s_add_i32 m0, s24, 0x2000
	s_nop 0
	global_load_lds_dwordx4 v[154:155], off
	s_waitcnt vmcnt(4)
	s_waitcnt lgkmcnt(0)
	s_barrier
	v_mfma_f32_16x16x32_bf16 v[64:67], v[134:137], v[218:221], v[64:67]
	v_mfma_f32_16x16x32_bf16 v[64:67], v[138:141], v[226:229], v[64:67]
	v_mfma_f32_16x16x32_bf16 v[48:51], v[138:141], v[230:233], v[48:51]
	v_mfma_f32_16x16x32_bf16 v[48:51], v[134:137], v[222:225], v[48:51]
	v_mfma_f32_16x16x32_bf16 v[32:35], v[134:137], v[234:237], v[32:35]
	v_mfma_f32_16x16x32_bf16 v[32:35], v[138:141], v[242:245], v[32:35]
	v_mfma_f32_16x16x32_bf16 v[16:19], v[138:141], v[246:249], v[16:19]
	v_mfma_f32_16x16x32_bf16 v[16:19], v[134:137], v[238:241], v[16:19]
	v_mfma_f32_16x16x32_bf16 v[12:15], v[142:145], v[238:241], v[12:15]
	v_mfma_f32_16x16x32_bf16 v[12:15], v[146:149], v[246:249], v[12:15]
	v_mfma_f32_16x16x32_bf16 v[28:31], v[146:149], v[242:245], v[28:31]
	v_mfma_f32_16x16x32_bf16 v[28:31], v[142:145], v[234:237], v[28:31]
	v_mfma_f32_16x16x32_bf16 v[44:47], v[142:145], v[222:225], v[44:47]
	v_mfma_f32_16x16x32_bf16 v[44:47], v[146:149], v[230:233], v[44:47]
	v_mfma_f32_16x16x32_bf16 v[60:63], v[146:149], v[226:229], v[60:63]
	v_mfma_f32_16x16x32_bf16 v[60:63], v[142:145], v[218:221], v[60:63]
	v_mfma_f32_16x16x32_bf16 v[56:59], v[150:153], v[218:221], v[56:59]
	v_mfma_f32_16x16x32_bf16 v[56:59], v[174:177], v[226:229], v[56:59]
	v_mfma_f32_16x16x32_bf16 v[40:43], v[174:177], v[230:233], v[40:43]
	v_mfma_f32_16x16x32_bf16 v[40:43], v[150:153], v[222:225], v[40:43]
	v_mfma_f32_16x16x32_bf16 v[24:27], v[150:153], v[234:237], v[24:27]
	v_mfma_f32_16x16x32_bf16 v[24:27], v[174:177], v[242:245], v[24:27]
	v_mfma_f32_16x16x32_bf16 v[8:11], v[174:177], v[246:249], v[8:11]
	v_mfma_f32_16x16x32_bf16 v[8:11], v[150:153], v[238:241], v[8:11]
	v_mfma_f32_16x16x32_bf16 v[4:7], v[178:181], v[238:241], v[4:7]
	v_mfma_f32_16x16x32_bf16 v[4:7], v[182:185], v[246:249], v[4:7]
	v_mfma_f32_16x16x32_bf16 v[20:23], v[182:185], v[242:245], v[20:23]
	v_mfma_f32_16x16x32_bf16 v[20:23], v[178:181], v[234:237], v[20:23]
	v_mfma_f32_16x16x32_bf16 v[36:39], v[178:181], v[222:225], v[36:39]
	v_mfma_f32_16x16x32_bf16 v[36:39], v[182:185], v[230:233], v[36:39]
	v_mfma_f32_16x16x32_bf16 v[52:55], v[182:185], v[226:229], v[52:55]
	v_mfma_f32_16x16x32_bf16 v[52:55], v[178:181], v[218:221], v[52:55]
	s_barrier
	s_add_i32 s94, s94, 2
	s_add_u32 vcc_lo, vcc_lo, 0x100
	s_addc_u32 vcc_hi, vcc_hi, 0
	s_cmp_gt_u32 s94, 13
	s_cbranch_scc0 .LBB0_384
	s_and_b64 vcc, exec, s[56:57]
	s_cbranch_vccz .LBB0_387
	s_barrier
	s_setprio 3

.LBB0_1135:
	ds_read_b128 v[168:171], v145
	ds_read_b128 v[174:177], v146
	ds_read_b128 v[178:181], v147
	ds_read_b128 v[182:185], v148
	ds_read_b128 v[194:197], v149
	ds_read_b128 v[198:201], v150
	ds_read_b128 v[202:205], v151
	ds_read_b128 v[206:209], v152
	s_add_u32 s70, s26, s68
	s_addc_u32 s71, s27, s69
	s_add_u32 s70, s70, 0x100
	s_addc_u32 s71, s71, 0
	s_add_u32 s84, s81, s68
	s_addc_u32 s85, s82, s69
	s_cmpk_eq_i32 s68, 0x700
	s_cselect_b32 s85, s59, s85
	s_cselect_b32 s84, s80, s84
	s_cselect_b32 s71, s57, s71
	s_cselect_b32 s70, s79, s70
	v_lshl_add_u64 v[140:141], v[138:139], 0, s[68:69]
	v_lshl_add_u64 v[242:243], v[140:141], 0, s[22:23]
	s_add_i32 m0, s34, 0x8000
	s_mov_b64 s[86:87], 0x20080
	ds_read_b128 v[210:213], v153
	ds_read_b128 v[214:217], v153 offset:2048
	ds_read_b128 v[218:221], v154
	ds_read_b128 v[222:225], v154 offset:2048
	ds_read_b128 v[226:229], v153 offset:4096
	ds_read_b128 v[230:233], v153 offset:6144
	ds_read_b128 v[234:237], v154 offset:4096
	ds_read_b128 v[238:241], v154 offset:6144
	global_load_lds_dwordx4 v[242:243], off
	v_lshl_add_u64 v[242:243], v[140:141], 0, s[86:87]
	s_add_i32 m0, s34, 0xa000
	s_mov_b64 s[86:87], 0x60080
	global_load_lds_dwordx4 v[242:243], off
	v_lshl_add_u64 v[242:243], v[140:141], 0, s[24:25]
	s_add_i32 m0, s34, 0xc000
	v_lshl_add_u64 v[140:141], v[140:141], 0, s[86:87]
	global_load_lds_dwordx4 v[242:243], off
	s_add_i32 m0, s34, 0xe000
	s_nop 0
	global_load_lds_dwordx4 v[140:141], off
	s_waitcnt vmcnt(8)
	s_waitcnt lgkmcnt(0)
	s_barrier
	v_mfma_f32_16x16x32_bf16 v[128:131], v[168:171], v[210:213], v[128:131]
	v_mfma_f32_16x16x32_bf16 v[128:131], v[174:177], v[218:221], v[128:131]
	v_mfma_f32_16x16x32_bf16 v[112:115], v[174:177], v[222:225], v[112:115]
	v_mfma_f32_16x16x32_bf16 v[112:115], v[168:171], v[214:217], v[112:115]
	v_mfma_f32_16x16x32_bf16 v[96:99], v[168:171], v[226:229], v[96:99]
	v_mfma_f32_16x16x32_bf16 v[96:99], v[174:177], v[234:237], v[96:99]
	v_mfma_f32_16x16x32_bf16 v[80:83], v[174:177], v[238:241], v[80:83]
	v_mfma_f32_16x16x32_bf16 v[80:83], v[168:171], v[230:233], v[80:83]
	v_mfma_f32_16x16x32_bf16 v[76:79], v[178:181], v[230:233], v[76:79]
	v_mfma_f32_16x16x32_bf16 v[76:79], v[182:185], v[238:241], v[76:79]
	v_mfma_f32_16x16x32_bf16 v[92:95], v[182:185], v[234:237], v[92:95]
	v_mfma_f32_16x16x32_bf16 v[92:95], v[178:181], v[226:229], v[92:95]
	v_mfma_f32_16x16x32_bf16 v[108:111], v[178:181], v[214:217], v[108:111]
	v_mfma_f32_16x16x32_bf16 v[108:111], v[182:185], v[222:225], v[108:111]
	v_mfma_f32_16x16x32_bf16 v[124:127], v[182:185], v[218:221], v[124:127]
	v_mfma_f32_16x16x32_bf16 v[124:127], v[178:181], v[210:213], v[124:127]
	v_mfma_f32_16x16x32_bf16 v[120:123], v[194:197], v[210:213], v[120:123]
	v_mfma_f32_16x16x32_bf16 v[120:123], v[198:201], v[218:221], v[120:123]
	v_mfma_f32_16x16x32_bf16 v[104:107], v[198:201], v[222:225], v[104:107]
	v_mfma_f32_16x16x32_bf16 v[104:107], v[194:197], v[214:217], v[104:107]
	v_mfma_f32_16x16x32_bf16 v[88:91], v[194:197], v[226:229], v[88:91]
	v_mfma_f32_16x16x32_bf16 v[88:91], v[198:201], v[234:237], v[88:91]
	v_mfma_f32_16x16x32_bf16 v[72:75], v[198:201], v[238:241], v[72:75]
	v_mfma_f32_16x16x32_bf16 v[72:75], v[194:197], v[230:233], v[72:75]
	v_mfma_f32_16x16x32_bf16 v[68:71], v[202:205], v[230:233], v[68:71]
	v_mfma_f32_16x16x32_bf16 v[68:71], v[206:209], v[238:241], v[68:71]
	v_mfma_f32_16x16x32_bf16 v[84:87], v[206:209], v[234:237], v[84:87]
	v_mfma_f32_16x16x32_bf16 v[84:87], v[202:205], v[226:229], v[84:87]
	v_mfma_f32_16x16x32_bf16 v[100:103], v[202:205], v[214:217], v[100:103]
	v_mfma_f32_16x16x32_bf16 v[100:103], v[206:209], v[222:225], v[100:103]
	v_mfma_f32_16x16x32_bf16 v[116:119], v[206:209], v[218:221], v[116:119]
	v_mfma_f32_16x16x32_bf16 v[116:119], v[202:205], v[210:213], v[116:119]
	s_barrier
	v_lshl_add_u64 v[140:141], s[84:85], 0, v[158:159]
	s_add_i32 s84, s67, s3
	s_mov_b32 m0, s84
	ds_read_b128 v[210:213], v153 offset:16384
	ds_read_b128 v[214:217], v153 offset:18432
	ds_read_b128 v[218:221], v154 offset:16384
	ds_read_b128 v[222:225], v154 offset:18432
	ds_read_b128 v[226:229], v153 offset:20480
	ds_read_b128 v[230:233], v153 offset:22528
	ds_read_b128 v[234:237], v154 offset:20480
	ds_read_b128 v[238:241], v154 offset:22528
	global_load_lds_dwordx4 v[140:141], off
	v_lshl_add_u64 v[242:243], v[140:141], 0, s[0:1]
	s_add_i32 m0, s84, 0x2000
	s_add_i32 s84, s72, s3
	global_load_lds_dwordx4 v[242:243], off
	v_lshl_add_u64 v[242:243], v[140:141], 0, s[12:13]
	s_mov_b32 m0, s84
	s_nop 0
	global_load_lds_dwordx4 v[242:243], off
	v_lshl_add_u64 v[242:243], v[140:141], 0, s[14:15]
	s_add_i32 m0, s84, 0x2000
	s_nop 0
	global_load_lds_dwordx4 v[242:243], off
	s_waitcnt vmcnt(4)
	s_waitcnt lgkmcnt(0)
	s_barrier
	v_mfma_f32_16x16x32_bf16 v[64:67], v[168:171], v[210:213], v[64:67]
	v_mfma_f32_16x16x32_bf16 v[64:67], v[174:177], v[218:221], v[64:67]
	v_mfma_f32_16x16x32_bf16 v[48:51], v[174:177], v[222:225], v[48:51]
	v_mfma_f32_16x16x32_bf16 v[48:51], v[168:171], v[214:217], v[48:51]
	v_mfma_f32_16x16x32_bf16 v[32:35], v[168:171], v[226:229], v[32:35]
	v_mfma_f32_16x16x32_bf16 v[32:35], v[174:177], v[234:237], v[32:35]
	v_mfma_f32_16x16x32_bf16 v[16:19], v[174:177], v[238:241], v[16:19]
	v_mfma_f32_16x16x32_bf16 v[16:19], v[168:171], v[230:233], v[16:19]
	v_mfma_f32_16x16x32_bf16 v[12:15], v[178:181], v[230:233], v[12:15]
	v_mfma_f32_16x16x32_bf16 v[12:15], v[182:185], v[238:241], v[12:15]
	v_mfma_f32_16x16x32_bf16 v[28:31], v[182:185], v[234:237], v[28:31]
	v_mfma_f32_16x16x32_bf16 v[28:31], v[178:181], v[226:229], v[28:31]
	v_mfma_f32_16x16x32_bf16 v[44:47], v[178:181], v[214:217], v[44:47]
	v_mfma_f32_16x16x32_bf16 v[44:47], v[182:185], v[222:225], v[44:47]
	v_mfma_f32_16x16x32_bf16 v[60:63], v[182:185], v[218:221], v[60:63]
	v_mfma_f32_16x16x32_bf16 v[60:63], v[178:181], v[210:213], v[60:63]
	v_mfma_f32_16x16x32_bf16 v[56:59], v[194:197], v[210:213], v[56:59]
	v_mfma_f32_16x16x32_bf16 v[56:59], v[198:201], v[218:221], v[56:59]
	v_mfma_f32_16x16x32_bf16 v[40:43], v[198:201], v[222:225], v[40:43]
	v_mfma_f32_16x16x32_bf16 v[40:43], v[194:197], v[214:217], v[40:43]
	v_mfma_f32_16x16x32_bf16 v[24:27], v[194:197], v[226:229], v[24:27]
	v_mfma_f32_16x16x32_bf16 v[24:27], v[198:201], v[234:237], v[24:27]
	v_mfma_f32_16x16x32_bf16 v[8:11], v[198:201], v[238:241], v[8:11]
	v_mfma_f32_16x16x32_bf16 v[8:11], v[194:197], v[230:233], v[8:11]
	v_mfma_f32_16x16x32_bf16 v[4:7], v[202:205], v[230:233], v[4:7]
	v_mfma_f32_16x16x32_bf16 v[4:7], v[206:209], v[238:241], v[4:7]
	v_mfma_f32_16x16x32_bf16 v[20:23], v[206:209], v[234:237], v[20:23]
	v_mfma_f32_16x16x32_bf16 v[20:23], v[202:205], v[226:229], v[20:23]
	v_mfma_f32_16x16x32_bf16 v[36:39], v[202:205], v[214:217], v[36:39]
	v_mfma_f32_16x16x32_bf16 v[36:39], v[206:209], v[222:225], v[36:39]
	v_mfma_f32_16x16x32_bf16 v[52:55], v[206:209], v[218:221], v[52:55]
	v_mfma_f32_16x16x32_bf16 v[52:55], v[202:205], v[210:213], v[52:55]
	s_barrier
	ds_read_b128 v[168:171], v163
	ds_read_b128 v[174:177], v164
	ds_read_b128 v[178:181], v155
	ds_read_b128 v[182:185], v160
	ds_read_b128 v[194:197], v165
	ds_read_b128 v[198:201], v166
	ds_read_b128 v[202:205], v161
	ds_read_b128 v[206:209], v162
	s_mov_b32 m0, s34
	v_lshl_add_u64 v[242:243], s[70:71], 0, v[0:1]
	ds_read_b128 v[210:213], v153 offset:32768
	ds_read_b128 v[214:217], v153 offset:34816
	ds_read_b128 v[218:221], v154 offset:32768
	ds_read_b128 v[222:225], v154 offset:34816
	ds_read_b128 v[226:229], v153 offset:36864
	ds_read_b128 v[230:233], v153 offset:38912
	ds_read_b128 v[234:237], v154 offset:36864
	ds_read_b128 v[238:241], v154 offset:38912
	global_load_lds_dwordx4 v[242:243], off
	v_lshl_add_u64 v[244:245], v[242:243], 0, s[16:17]
	s_mov_b32 m0, s35
	s_nop 0
	global_load_lds_dwordx4 v[244:245], off
	v_lshl_add_u64 v[244:245], v[242:243], 0, s[0:1]
	s_mov_b32 m0, s38
	v_lshl_add_u64 v[242:243], v[242:243], 0, s[18:19]
	global_load_lds_dwordx4 v[244:245], off
	s_mov_b32 m0, s39
	s_nop 0
	global_load_lds_dwordx4 v[242:243], off
	s_waitcnt vmcnt(8)
	s_waitcnt lgkmcnt(0)
	s_barrier
	v_mfma_f32_16x16x32_bf16 v[128:131], v[168:171], v[210:213], v[128:131]
	v_mfma_f32_16x16x32_bf16 v[128:131], v[174:177], v[218:221], v[128:131]
	v_mfma_f32_16x16x32_bf16 v[112:115], v[174:177], v[222:225], v[112:115]
	v_mfma_f32_16x16x32_bf16 v[112:115], v[168:171], v[214:217], v[112:115]
	v_mfma_f32_16x16x32_bf16 v[96:99], v[168:171], v[226:229], v[96:99]
	v_mfma_f32_16x16x32_bf16 v[96:99], v[174:177], v[234:237], v[96:99]
	v_mfma_f32_16x16x32_bf16 v[80:83], v[174:177], v[238:241], v[80:83]
	v_mfma_f32_16x16x32_bf16 v[80:83], v[168:171], v[230:233], v[80:83]
	v_mfma_f32_16x16x32_bf16 v[76:79], v[178:181], v[230:233], v[76:79]
	v_mfma_f32_16x16x32_bf16 v[76:79], v[182:185], v[238:241], v[76:79]
	v_mfma_f32_16x16x32_bf16 v[92:95], v[182:185], v[234:237], v[92:95]
	v_mfma_f32_16x16x32_bf16 v[92:95], v[178:181], v[226:229], v[92:95]
	v_mfma_f32_16x16x32_bf16 v[108:111], v[178:181], v[214:217], v[108:111]
	v_mfma_f32_16x16x32_bf16 v[108:111], v[182:185], v[222:225], v[108:111]
	v_mfma_f32_16x16x32_bf16 v[124:127], v[182:185], v[218:221], v[124:127]
	v_mfma_f32_16x16x32_bf16 v[124:127], v[178:181], v[210:213], v[124:127]
	v_mfma_f32_16x16x32_bf16 v[120:123], v[194:197], v[210:213], v[120:123]
	v_mfma_f32_16x16x32_bf16 v[120:123], v[198:201], v[218:221], v[120:123]
	v_mfma_f32_16x16x32_bf16 v[104:107], v[198:201], v[222:225], v[104:107]
	v_mfma_f32_16x16x32_bf16 v[104:107], v[194:197], v[214:217], v[104:107]
	v_mfma_f32_16x16x32_bf16 v[88:91], v[194:197], v[226:229], v[88:91]
	v_mfma_f32_16x16x32_bf16 v[88:91], v[198:201], v[234:237], v[88:91]
	v_mfma_f32_16x16x32_bf16 v[72:75], v[198:201], v[238:241], v[72:75]
	v_mfma_f32_16x16x32_bf16 v[72:75], v[194:197], v[230:233], v[72:75]
	v_mfma_f32_16x16x32_bf16 v[68:71], v[202:205], v[230:233], v[68:71]
	v_mfma_f32_16x16x32_bf16 v[68:71], v[206:209], v[238:241], v[68:71]
	v_mfma_f32_16x16x32_bf16 v[84:87], v[206:209], v[234:237], v[84:87]
	v_mfma_f32_16x16x32_bf16 v[84:87], v[202:205], v[226:229], v[84:87]
	v_mfma_f32_16x16x32_bf16 v[100:103], v[202:205], v[214:217], v[100:103]
	v_mfma_f32_16x16x32_bf16 v[100:103], v[206:209], v[222:225], v[100:103]
	v_mfma_f32_16x16x32_bf16 v[116:119], v[206:209], v[218:221], v[116:119]
	v_mfma_f32_16x16x32_bf16 v[116:119], v[202:205], v[210:213], v[116:119]
	s_barrier
	s_add_i32 s70, s73, s3
	v_lshl_add_u64 v[242:243], v[140:141], 0, s[22:23]
	s_mov_b32 m0, s70
	ds_read_b128 v[210:213], v153 offset:49152
	ds_read_b128 v[214:217], v153 offset:51200
	ds_read_b128 v[218:221], v154 offset:49152
	ds_read_b128 v[222:225], v154 offset:51200
	ds_read_b128 v[226:229], v153 offset:53248
	ds_read_b128 v[230:233], v153 offset:55296
	ds_read_b128 v[234:237], v154 offset:53248
	ds_read_b128 v[238:241], v154 offset:55296
	global_load_lds_dwordx4 v[242:243], off
	v_lshl_add_u64 v[242:243], v[140:141], 0, s[24:25]
	s_add_i32 m0, s70, 0x2000
	s_add_i32 s70, s77, s3
	global_load_lds_dwordx4 v[242:243], off
	v_lshl_add_u64 v[242:243], v[140:141], 0, s[28:29]
	s_mov_b32 m0, s70
	v_lshl_add_u64 v[140:141], v[140:141], 0, s[36:37]
	global_load_lds_dwordx4 v[242:243], off
	s_add_i32 m0, s70, 0x2000
	s_nop 0
	global_load_lds_dwordx4 v[140:141], off
	s_waitcnt vmcnt(4)
	s_waitcnt lgkmcnt(0)
	s_barrier
	v_mfma_f32_16x16x32_bf16 v[64:67], v[168:171], v[210:213], v[64:67]
	v_mfma_f32_16x16x32_bf16 v[64:67], v[174:177], v[218:221], v[64:67]
	v_mfma_f32_16x16x32_bf16 v[48:51], v[174:177], v[222:225], v[48:51]
	v_mfma_f32_16x16x32_bf16 v[48:51], v[168:171], v[214:217], v[48:51]
	v_mfma_f32_16x16x32_bf16 v[32:35], v[168:171], v[226:229], v[32:35]
	v_mfma_f32_16x16x32_bf16 v[32:35], v[174:177], v[234:237], v[32:35]
	v_mfma_f32_16x16x32_bf16 v[16:19], v[174:177], v[238:241], v[16:19]
	v_mfma_f32_16x16x32_bf16 v[16:19], v[168:171], v[230:233], v[16:19]
	v_mfma_f32_16x16x32_bf16 v[12:15], v[178:181], v[230:233], v[12:15]
	v_mfma_f32_16x16x32_bf16 v[12:15], v[182:185], v[238:241], v[12:15]
	v_mfma_f32_16x16x32_bf16 v[28:31], v[182:185], v[234:237], v[28:31]
	v_mfma_f32_16x16x32_bf16 v[28:31], v[178:181], v[226:229], v[28:31]
	v_mfma_f32_16x16x32_bf16 v[44:47], v[178:181], v[214:217], v[44:47]
	v_mfma_f32_16x16x32_bf16 v[44:47], v[182:185], v[222:225], v[44:47]
	v_mfma_f32_16x16x32_bf16 v[60:63], v[182:185], v[218:221], v[60:63]
	v_mfma_f32_16x16x32_bf16 v[60:63], v[178:181], v[210:213], v[60:63]
	v_mfma_f32_16x16x32_bf16 v[56:59], v[194:197], v[210:213], v[56:59]
	v_mfma_f32_16x16x32_bf16 v[56:59], v[198:201], v[218:221], v[56:59]
	v_mfma_f32_16x16x32_bf16 v[40:43], v[198:201], v[222:225], v[40:43]
	v_mfma_f32_16x16x32_bf16 v[40:43], v[194:197], v[214:217], v[40:43]
	v_mfma_f32_16x16x32_bf16 v[24:27], v[194:197], v[226:229], v[24:27]
	v_mfma_f32_16x16x32_bf16 v[24:27], v[198:201], v[234:237], v[24:27]
	v_mfma_f32_16x16x32_bf16 v[8:11], v[198:201], v[238:241], v[8:11]
	v_mfma_f32_16x16x32_bf16 v[8:11], v[194:197], v[230:233], v[8:11]
	v_mfma_f32_16x16x32_bf16 v[4:7], v[202:205], v[230:233], v[4:7]
	v_mfma_f32_16x16x32_bf16 v[4:7], v[206:209], v[238:241], v[4:7]
	v_mfma_f32_16x16x32_bf16 v[20:23], v[206:209], v[234:237], v[20:23]
	v_mfma_f32_16x16x32_bf16 v[20:23], v[202:205], v[226:229], v[20:23]
	v_mfma_f32_16x16x32_bf16 v[36:39], v[202:205], v[214:217], v[36:39]
	v_mfma_f32_16x16x32_bf16 v[36:39], v[206:209], v[222:225], v[36:39]
	v_mfma_f32_16x16x32_bf16 v[52:55], v[206:209], v[218:221], v[52:55]
	v_mfma_f32_16x16x32_bf16 v[52:55], v[202:205], v[210:213], v[52:55]
	s_barrier
	s_add_i32 s83, s83, 2
	s_add_u32 s68, s68, 0x100
	s_addc_u32 s69, s69, 0
	s_cmp_gt_u32 s83, 13
	s_cbranch_scc0 .LBB0_1135
	s_and_b64 vcc, exec, s[40:41]
	s_cbranch_vccz .LBB0_1138
	s_barrier
	s_setprio 3
